# attention online softmax: running max only advanced when the tile max exceeds it by more than 8 (log2 units), so the O/l rescale branch is mostly skipped; exact softmax identity, f32 accumulators unch
# speedup vs baseline: 1.0019x; 1.0019x over previous
.LBB0_459:
	ds_read_b64_tr_b16 v[188:189], v153 offset:9216
	ds_read_b64_tr_b16 v[190:191], v153 offset:9984
	ds_read_b64_tr_b16 v[192:193], v153 offset:9280
	ds_read_b64_tr_b16 v[194:195], v153 offset:10048
	ds_read_b64_tr_b16 v[196:197], v153 offset:12288
	ds_read_b64_tr_b16 v[198:199], v153 offset:13056
	ds_read_b64_tr_b16 v[200:201], v153 offset:12352
	ds_read_b64_tr_b16 v[202:203], v153 offset:13120
	ds_read_b64_tr_b16 v[204:205], v153 offset:15360
	ds_read_b64_tr_b16 v[206:207], v153 offset:16128
	ds_read_b64_tr_b16 v[208:209], v153 offset:15424
	ds_read_b64_tr_b16 v[210:211], v153 offset:16192
	ds_read_b64_tr_b16 v[212:213], v153 offset:18432
	ds_read_b64_tr_b16 v[214:215], v153 offset:19200
	ds_read_b64_tr_b16 v[216:217], v153 offset:18496
	ds_read_b64_tr_b16 v[218:219], v153 offset:19264
	s_nop 0
	v_max_f32_e32 v2, v147, v147
	s_nop 2
	v_max_f32_e32 v50, v146, v146
	v_max_f32_e32 v2, v50, v2
	v_max3_f32 v2, v2, v144, v145
	v_max3_f32 v2, v2, v142, v143
	v_max3_f32 v2, v2, v140, v141
	v_max3_f32 v2, v2, v138, v139
	v_max3_f32 v2, v2, v134, v135
	v_max3_f32 v2, v2, v130, v131
	v_max3_f32 v2, v2, v16, v17
	v_max3_f32 v2, v2, v136, v137
	v_max3_f32 v2, v2, v132, v133
	v_max3_f32 v2, v2, v14, v15
	v_max3_f32 v2, v2, v12, v13
	v_max3_f32 v2, v2, v10, v11
	v_max3_f32 v2, v2, v8, v9
	v_max3_f32 v2, v2, v6, v7
	v_max3_f32 v2, v2, v4, v5
	v_mov_b32_e32 v50, v2
	s_nop 1
	v_permlane32_swap_b32_e32 v50, v2
	v_max3_f32 v50, v173, v2, v50
	v_add_f32_e32 v2, 0x41000000, v173
	v_cmp_gt_f32_e32 vcc, v50, v2
	s_nop 1
	v_cndmask_b32_e32 v50, v173, v50, vcc
	v_sub_f32_e32 v2, v173, v50
	v_exp_f32_e32 v2, v2
	s_nop 0
	v_cmp_neq_f32_e32 vcc, 1.0, v2
	s_cbranch_vccz .LBB0_461
	v_pk_mul_f32 v[48:49], v[48:49], v[2:3] op_sel_hi:[1,0]
	v_pk_mul_f32 v[46:47], v[46:47], v[2:3] op_sel_hi:[1,0]
	v_pk_mul_f32 v[44:45], v[44:45], v[2:3] op_sel_hi:[1,0]
	v_pk_mul_f32 v[42:43], v[42:43], v[2:3] op_sel_hi:[1,0]
	v_pk_mul_f32 v[40:41], v[40:41], v[2:3] op_sel_hi:[1,0]
	v_pk_mul_f32 v[38:39], v[38:39], v[2:3] op_sel_hi:[1,0]
	v_pk_mul_f32 v[36:37], v[36:37], v[2:3] op_sel_hi:[1,0]
	v_pk_mul_f32 v[34:35], v[34:35], v[2:3] op_sel_hi:[1,0]
	v_pk_mul_f32 v[32:33], v[32:33], v[2:3] op_sel_hi:[1,0]
	v_pk_mul_f32 v[30:31], v[30:31], v[2:3] op_sel_hi:[1,0]
	v_pk_mul_f32 v[28:29], v[28:29], v[2:3] op_sel_hi:[1,0]
	v_pk_mul_f32 v[26:27], v[26:27], v[2:3] op_sel_hi:[1,0]
	v_pk_mul_f32 v[24:25], v[24:25], v[2:3] op_sel_hi:[1,0]
	v_pk_mul_f32 v[22:23], v[22:23], v[2:3] op_sel_hi:[1,0]
	v_pk_mul_f32 v[20:21], v[20:21], v[2:3] op_sel_hi:[1,0]
	v_pk_mul_f32 v[18:19], v[18:19], v[2:3] op_sel_hi:[1,0]

.LBB0_1611:
	v_lshl_add_u64 v[66:67], v[214:215], 0, s[56:57]
	v_cndmask_b32_e64 v67, v217, v67, s[4:5]
	v_cndmask_b32_e64 v66, v216, v66, s[4:5]
	s_waitcnt vmcnt(63) expcnt(7) lgkmcnt(15)
	s_barrier
	s_waitcnt vmcnt(4)
	ds_write_b128 v229, v[146:149]
	s_waitcnt vmcnt(3)
	ds_write_b128 v230, v[150:153]
	s_waitcnt vmcnt(2)
	ds_write_b128 v231, v[154:157]
	s_waitcnt vmcnt(1)
	ds_write_b128 v232, v[162:165] offset:25600
	s_waitcnt vmcnt(0)
	ds_write_b128 v233, v[158:161] offset:25600
	s_waitcnt lgkmcnt(0)
	s_barrier
	global_load_dwordx4 v[146:149], v[66:67], off
	v_lshl_add_u64 v[66:67], v[210:211], 0, s[56:57]
	v_cndmask_b32_e64 v67, v213, v67, s[8:9]
	v_cndmask_b32_e64 v66, v212, v66, s[8:9]
	global_load_dwordx4 v[150:153], v[66:67], off
	v_lshl_add_u64 v[66:67], v[206:207], 0, s[56:57]
	v_cndmask_b32_e64 v67, v209, v67, s[12:13]
	v_cndmask_b32_e64 v66, v208, v66, s[12:13]
	global_load_dwordx4 v[154:157], v[66:67], off
	v_lshl_add_u64 v[66:67], v[204:205], 0, s[56:57]
	v_lshl_add_u64 v[68:69], v[202:203], 0, s[56:57]
	global_load_dwordx4 v[162:165], v[66:67], off
	global_load_dwordx4 v[158:161], v[68:69], off
	s_cmp_gt_i32 s58, s29
	s_cbranch_scc1 .LBB0_1615
	v_add_u32_e32 v235, v226, v225
	ds_read_b128 v[66:69], v235
	ds_read_b128 v[236:239], v235 offset:32
	ds_read_b128 v[70:73], v235 offset:12800
	ds_read_b128 v[244:247], v235 offset:12832
	s_waitcnt lgkmcnt(3)
	v_mfma_f32_32x32x16_bf16 v[82:97], v[66:69], v[142:145], 0
	ds_read_b128 v[248:251], v235 offset:64
	ds_read_b128 v[252:255], v235 offset:12864
	s_waitcnt lgkmcnt(3)
	v_mfma_f32_32x32x16_bf16 v[66:81], v[70:73], v[142:145], 0
	v_mfma_f32_32x32x16_bf16 v[82:97], v[236:239], v[138:141], v[82:97]
	s_waitcnt lgkmcnt(2)
	v_mfma_f32_32x32x16_bf16 v[66:81], v[244:247], v[138:141], v[66:81]
	ds_read_b128 v[236:239], v235 offset:96
	ds_read_b128 v[244:247], v235 offset:12896
	s_waitcnt lgkmcnt(3)
	v_mfma_f32_32x32x16_bf16 v[82:97], v[248:251], v[134:137], v[82:97]
	s_waitcnt lgkmcnt(2)
	v_mfma_f32_32x32x16_bf16 v[66:81], v[252:255], v[134:137], v[66:81]
	ds_read_b128 v[248:251], v235 offset:128
	ds_read_b128 v[252:255], v235 offset:12928
	s_waitcnt lgkmcnt(3)
	v_mfma_f32_32x32x16_bf16 v[82:97], v[236:239], v[130:133], v[82:97]
	s_waitcnt lgkmcnt(2)
	v_mfma_f32_32x32x16_bf16 v[66:81], v[244:247], v[130:133], v[66:81]
	ds_read_b128 v[236:239], v235 offset:160
	ds_read_b128 v[244:247], v235 offset:12960
	s_waitcnt lgkmcnt(3)
	v_mfma_f32_32x32x16_bf16 v[82:97], v[248:251], v[126:129], v[82:97]
	s_waitcnt lgkmcnt(2)
	v_mfma_f32_32x32x16_bf16 v[66:81], v[252:255], v[126:129], v[66:81]
	ds_read_b128 v[248:251], v235 offset:192
	ds_read_b128 v[252:255], v235 offset:12992
	s_waitcnt lgkmcnt(3)
	v_mfma_f32_32x32x16_bf16 v[82:97], v[236:239], v[122:125], v[82:97]
	s_waitcnt lgkmcnt(2)
	v_mfma_f32_32x32x16_bf16 v[66:81], v[244:247], v[122:125], v[66:81]
	ds_read_b128 v[236:239], v235 offset:224
	ds_read_b128 v[244:247], v235 offset:13024
	s_waitcnt lgkmcnt(3)
	v_mfma_f32_32x32x16_bf16 v[82:97], v[248:251], v[118:121], v[82:97]
	s_waitcnt lgkmcnt(2)
	v_mfma_f32_32x32x16_bf16 v[66:81], v[252:255], v[118:121], v[66:81]
	ds_read_b128 v[248:251], v235 offset:256
	ds_read_b128 v[252:255], v235 offset:13056
	s_waitcnt lgkmcnt(3)
	v_mfma_f32_32x32x16_bf16 v[82:97], v[236:239], v[114:117], v[82:97]
	s_waitcnt lgkmcnt(2)
	v_mfma_f32_32x32x16_bf16 v[66:81], v[244:247], v[114:117], v[66:81]
	ds_read_b128 v[236:239], v235 offset:288
	ds_read_b128 v[244:247], v235 offset:13088
	s_waitcnt lgkmcnt(3)
	v_mfma_f32_32x32x16_bf16 v[82:97], v[248:251], v[110:113], v[82:97]
	s_waitcnt lgkmcnt(2)
	v_mfma_f32_32x32x16_bf16 v[66:81], v[252:255], v[110:113], v[66:81]
	ds_read_b128 v[248:251], v235 offset:320
	ds_read_b128 v[252:255], v235 offset:13120
	s_waitcnt lgkmcnt(3)
	v_mfma_f32_32x32x16_bf16 v[82:97], v[236:239], v[106:109], v[82:97]
	s_waitcnt lgkmcnt(2)
	v_mfma_f32_32x32x16_bf16 v[66:81], v[244:247], v[106:109], v[66:81]
	ds_read_b128 v[236:239], v235 offset:352
	ds_read_b128 v[244:247], v235 offset:13152
	s_waitcnt lgkmcnt(3)
	v_mfma_f32_32x32x16_bf16 v[82:97], v[248:251], v[102:105], v[82:97]
	s_waitcnt lgkmcnt(2)
	v_mfma_f32_32x32x16_bf16 v[66:81], v[252:255], v[102:105], v[66:81]
	s_waitcnt lgkmcnt(1)
	v_mfma_f32_32x32x16_bf16 v[82:97], v[236:239], v[98:101], v[82:97]
	s_waitcnt lgkmcnt(0)
	v_mfma_f32_32x32x16_bf16 v[66:81], v[244:247], v[98:101], v[66:81]
	s_nop 9
	v_max_f32_e32 v235, v83, v83
	v_max_f32_e32 v236, v82, v82
	v_max_f32_e32 v235, v236, v235
	v_max3_f32 v235, v235, v84, v85
	v_max3_f32 v235, v235, v86, v87
	v_max3_f32 v235, v235, v88, v89
	v_max3_f32 v235, v235, v90, v91
	v_max3_f32 v235, v235, v92, v93
	v_max3_f32 v235, v235, v94, v95
	v_max3_f32 v235, v235, v96, v97
	v_max3_f32 v235, v235, v66, v67
	v_max3_f32 v235, v235, v68, v69
	v_max3_f32 v235, v235, v70, v71
	v_max3_f32 v235, v235, v72, v73
	v_max3_f32 v235, v235, v74, v75
	v_max3_f32 v235, v235, v76, v77
	v_max3_f32 v235, v235, v78, v79
	v_max3_f32 v235, v235, v80, v81
	v_mov_b32_e32 v236, v235
	s_nop 1
	v_permlane32_swap_b32_e32 v236, v235
	s_waitcnt lgkmcnt(0)
	v_max3_f32 v235, v218, v235, v236
	v_add_f32_e32 v236, 0x41000000, v218
	v_cmp_gt_f32_e32 vcc, v235, v236
	s_nop 1
	v_cndmask_b32_e32 v235, v218, v235, vcc
	v_sub_f32_e32 v218, v218, v235
	v_exp_f32_e32 v218, v218
	s_nop 0
	v_cmp_neq_f32_e32 vcc, 1.0, v218
	s_cbranch_vccz .LBB0_1614
	v_pk_mul_f32 v[64:65], v[64:65], v[218:219] op_sel_hi:[1,0]
	v_pk_mul_f32 v[62:63], v[62:63], v[218:219] op_sel_hi:[1,0]
	v_pk_mul_f32 v[60:61], v[60:61], v[218:219] op_sel_hi:[1,0]
	v_pk_mul_f32 v[58:59], v[58:59], v[218:219] op_sel_hi:[1,0]
	v_pk_mul_f32 v[56:57], v[56:57], v[218:219] op_sel_hi:[1,0]
	v_pk_mul_f32 v[54:55], v[54:55], v[218:219] op_sel_hi:[1,0]
	v_pk_mul_f32 v[52:53], v[52:53], v[218:219] op_sel_hi:[1,0]
	v_pk_mul_f32 v[50:51], v[50:51], v[218:219] op_sel_hi:[1,0]
	v_pk_mul_f32 v[48:49], v[48:49], v[218:219] op_sel_hi:[1,0]
	v_pk_mul_f32 v[46:47], v[46:47], v[218:219] op_sel_hi:[1,0]
	v_pk_mul_f32 v[44:45], v[44:45], v[218:219] op_sel_hi:[1,0]
	v_pk_mul_f32 v[42:43], v[42:43], v[218:219] op_sel_hi:[1,0]
	v_pk_mul_f32 v[40:41], v[40:41], v[218:219] op_sel_hi:[1,0]
	v_pk_mul_f32 v[38:39], v[38:39], v[218:219] op_sel_hi:[1,0]
	v_pk_mul_f32 v[36:37], v[36:37], v[218:219] op_sel_hi:[1,0]
	v_pk_mul_f32 v[34:35], v[34:35], v[218:219] op_sel_hi:[1,0]
	v_pk_mul_f32 v[32:33], v[32:33], v[218:219] op_sel_hi:[1,0]
	v_pk_mul_f32 v[30:31], v[30:31], v[218:219] op_sel_hi:[1,0]
	v_pk_mul_f32 v[28:29], v[28:29], v[218:219] op_sel_hi:[1,0]
	v_pk_mul_f32 v[26:27], v[26:27], v[218:219] op_sel_hi:[1,0]
	v_pk_mul_f32 v[24:25], v[24:25], v[218:219] op_sel_hi:[1,0]
	v_pk_mul_f32 v[22:23], v[22:23], v[218:219] op_sel_hi:[1,0]
	v_pk_mul_f32 v[20:21], v[20:21], v[218:219] op_sel_hi:[1,0]
	v_pk_mul_f32 v[18:19], v[18:19], v[218:219] op_sel_hi:[1,0]
	v_pk_mul_f32 v[16:17], v[16:17], v[218:219] op_sel_hi:[1,0]
	v_pk_mul_f32 v[14:15], v[14:15], v[218:219] op_sel_hi:[1,0]
	v_pk_mul_f32 v[12:13], v[12:13], v[218:219] op_sel_hi:[1,0]
	v_pk_mul_f32 v[10:11], v[10:11], v[218:219] op_sel_hi:[1,0]
	v_pk_mul_f32 v[8:9], v[8:9], v[218:219] op_sel_hi:[1,0]
	v_pk_mul_f32 v[6:7], v[6:7], v[218:219] op_sel_hi:[1,0]
	v_pk_mul_f32 v[4:5], v[4:5], v[218:219] op_sel_hi:[1,0]
	v_pk_mul_f32 v[2:3], v[2:3], v[218:219] op_sel_hi:[1,0]

.LBB0_1618:
	s_andn2_b64 vcc, exec, s[48:49]
	s_barrier
	s_waitcnt vmcnt(4)
	ds_write_b128 v229, v[146:149]
	s_waitcnt vmcnt(3)
	ds_write_b128 v230, v[150:153]
	s_waitcnt vmcnt(2)
	ds_write_b128 v231, v[154:157]
	s_waitcnt vmcnt(1)
	ds_write_b128 v232, v[162:165] offset:25600
	s_waitcnt vmcnt(0)
	ds_write_b128 v233, v[158:161] offset:25600
	s_waitcnt lgkmcnt(0)
	s_barrier
	s_cbranch_vccnz .LBB0_1597
	v_add_u32_e32 v162, v226, v225
	ds_read_b128 v[66:69], v162
	ds_read_b128 v[146:149], v162 offset:32
	ds_read_b128 v[70:73], v162 offset:12800
	ds_read_b128 v[150:153], v162 offset:12832
	s_waitcnt lgkmcnt(3)
	v_mfma_f32_32x32x16_bf16 v[82:97], v[66:69], v[142:145], 0
	ds_read_b128 v[154:157], v162 offset:64
	ds_read_b128 v[158:161], v162 offset:12864
	s_waitcnt lgkmcnt(3)
	v_mfma_f32_32x32x16_bf16 v[66:81], v[70:73], v[142:145], 0
	v_mfma_f32_32x32x16_bf16 v[82:97], v[146:149], v[138:141], v[82:97]
	ds_read_b128 v[142:145], v162 offset:96
	ds_read_b128 v[146:149], v162 offset:12896
	s_waitcnt lgkmcnt(4)
	v_mfma_f32_32x32x16_bf16 v[66:81], v[150:153], v[138:141], v[66:81]
	s_waitcnt lgkmcnt(3)
	v_mfma_f32_32x32x16_bf16 v[82:97], v[154:157], v[134:137], v[82:97]
	ds_read_b128 v[138:141], v162 offset:128
	ds_read_b128 v[150:153], v162 offset:12928
	s_waitcnt lgkmcnt(4)
	v_mfma_f32_32x32x16_bf16 v[66:81], v[158:161], v[134:137], v[66:81]
	s_waitcnt lgkmcnt(3)
	v_mfma_f32_32x32x16_bf16 v[82:97], v[142:145], v[130:133], v[82:97]
	ds_read_b128 v[134:137], v162 offset:160
	ds_read_b128 v[142:145], v162 offset:12960
	s_waitcnt lgkmcnt(4)
	v_mfma_f32_32x32x16_bf16 v[66:81], v[146:149], v[130:133], v[66:81]
	s_waitcnt lgkmcnt(3)
	v_mfma_f32_32x32x16_bf16 v[82:97], v[138:141], v[126:129], v[82:97]
	ds_read_b128 v[130:133], v162 offset:192
	ds_read_b128 v[138:141], v162 offset:12992
	s_waitcnt lgkmcnt(4)
	v_mfma_f32_32x32x16_bf16 v[66:81], v[150:153], v[126:129], v[66:81]
	s_waitcnt lgkmcnt(3)
	v_mfma_f32_32x32x16_bf16 v[82:97], v[134:137], v[122:125], v[82:97]
	ds_read_b128 v[126:129], v162 offset:224
	ds_read_b128 v[134:137], v162 offset:13024
	s_waitcnt lgkmcnt(4)
	v_mfma_f32_32x32x16_bf16 v[66:81], v[142:145], v[122:125], v[66:81]
	s_waitcnt lgkmcnt(3)
	v_mfma_f32_32x32x16_bf16 v[82:97], v[130:133], v[118:121], v[82:97]
	ds_read_b128 v[122:125], v162 offset:256
	ds_read_b128 v[130:133], v162 offset:13056
	s_waitcnt lgkmcnt(4)
	v_mfma_f32_32x32x16_bf16 v[66:81], v[138:141], v[118:121], v[66:81]
	s_waitcnt lgkmcnt(3)
	v_mfma_f32_32x32x16_bf16 v[82:97], v[126:129], v[114:117], v[82:97]
	ds_read_b128 v[118:121], v162 offset:288
	ds_read_b128 v[126:129], v162 offset:13088
	s_waitcnt lgkmcnt(4)
	v_mfma_f32_32x32x16_bf16 v[66:81], v[134:137], v[114:117], v[66:81]
	s_waitcnt lgkmcnt(3)
	v_mfma_f32_32x32x16_bf16 v[82:97], v[122:125], v[110:113], v[82:97]
	ds_read_b128 v[114:117], v162 offset:320
	ds_read_b128 v[122:125], v162 offset:13120
	s_waitcnt lgkmcnt(4)
	v_mfma_f32_32x32x16_bf16 v[66:81], v[130:133], v[110:113], v[66:81]
	s_waitcnt lgkmcnt(3)
	v_mfma_f32_32x32x16_bf16 v[82:97], v[118:121], v[106:109], v[82:97]
	ds_read_b128 v[110:113], v162 offset:352
	ds_read_b128 v[118:121], v162 offset:13152
	s_waitcnt lgkmcnt(4)
	v_mfma_f32_32x32x16_bf16 v[66:81], v[126:129], v[106:109], v[66:81]
	s_waitcnt lgkmcnt(3)
	v_mfma_f32_32x32x16_bf16 v[82:97], v[114:117], v[102:105], v[82:97]
	s_waitcnt lgkmcnt(2)
	v_mfma_f32_32x32x16_bf16 v[66:81], v[122:125], v[102:105], v[66:81]
	s_waitcnt lgkmcnt(1)
	v_mfma_f32_32x32x16_bf16 v[82:97], v[110:113], v[98:101], v[82:97]
	s_waitcnt lgkmcnt(0)
	v_mfma_f32_32x32x16_bf16 v[66:81], v[118:121], v[98:101], v[66:81]
	s_nop 9
	v_max_f32_e32 v98, v83, v83
	v_max_f32_e32 v99, v82, v82
	v_max_f32_e32 v98, v99, v98
	v_max3_f32 v98, v98, v84, v85
	v_max3_f32 v98, v98, v86, v87
	v_max3_f32 v98, v98, v88, v89
	v_max3_f32 v98, v98, v90, v91
	v_max3_f32 v98, v98, v92, v93
	v_max3_f32 v98, v98, v94, v95
	v_max3_f32 v98, v98, v96, v97
	v_max3_f32 v98, v98, v66, v67
	v_max3_f32 v98, v98, v68, v69
	v_max3_f32 v98, v98, v70, v71
	v_max3_f32 v98, v98, v72, v73
	v_max3_f32 v98, v98, v74, v75
	v_max3_f32 v98, v98, v76, v77
	v_max3_f32 v98, v98, v78, v79
	v_max3_f32 v98, v98, v80, v81
	v_mov_b32_e32 v99, v98
	s_nop 1
	v_permlane32_swap_b32_e32 v99, v98
	s_waitcnt lgkmcnt(0)
	v_max3_f32 v99, v235, v98, v99
	v_add_f32_e32 v98, 0x41000000, v235
	v_cmp_gt_f32_e32 vcc, v99, v98
	s_nop 1
	v_cndmask_b32_e32 v99, v235, v99, vcc
	v_sub_f32_e32 v98, v235, v99
	v_exp_f32_e32 v98, v98
	s_nop 0
	v_cmp_neq_f32_e32 vcc, 1.0, v98
	s_cbranch_vccz .LBB0_1596
	v_pk_mul_f32 v[64:65], v[64:65], v[98:99] op_sel_hi:[1,0]
	v_pk_mul_f32 v[62:63], v[62:63], v[98:99] op_sel_hi:[1,0]
	v_pk_mul_f32 v[60:61], v[60:61], v[98:99] op_sel_hi:[1,0]
	v_pk_mul_f32 v[58:59], v[58:59], v[98:99] op_sel_hi:[1,0]
	v_pk_mul_f32 v[56:57], v[56:57], v[98:99] op_sel_hi:[1,0]
	v_pk_mul_f32 v[54:55], v[54:55], v[98:99] op_sel_hi:[1,0]
	v_pk_mul_f32 v[52:53], v[52:53], v[98:99] op_sel_hi:[1,0]
	v_pk_mul_f32 v[50:51], v[50:51], v[98:99] op_sel_hi:[1,0]
	v_pk_mul_f32 v[48:49], v[48:49], v[98:99] op_sel_hi:[1,0]
	v_pk_mul_f32 v[46:47], v[46:47], v[98:99] op_sel_hi:[1,0]
	v_pk_mul_f32 v[44:45], v[44:45], v[98:99] op_sel_hi:[1,0]
	v_pk_mul_f32 v[42:43], v[42:43], v[98:99] op_sel_hi:[1,0]
	v_pk_mul_f32 v[40:41], v[40:41], v[98:99] op_sel_hi:[1,0]
	v_pk_mul_f32 v[38:39], v[38:39], v[98:99] op_sel_hi:[1,0]
	v_pk_mul_f32 v[36:37], v[36:37], v[98:99] op_sel_hi:[1,0]
	v_pk_mul_f32 v[34:35], v[34:35], v[98:99] op_sel_hi:[1,0]
	v_pk_mul_f32 v[32:33], v[32:33], v[98:99] op_sel_hi:[1,0]
	v_pk_mul_f32 v[30:31], v[30:31], v[98:99] op_sel_hi:[1,0]
	v_pk_mul_f32 v[28:29], v[28:29], v[98:99] op_sel_hi:[1,0]
	v_pk_mul_f32 v[26:27], v[26:27], v[98:99] op_sel_hi:[1,0]
	v_pk_mul_f32 v[24:25], v[24:25], v[98:99] op_sel_hi:[1,0]
	v_pk_mul_f32 v[22:23], v[22:23], v[98:99] op_sel_hi:[1,0]
	v_pk_mul_f32 v[20:21], v[20:21], v[98:99] op_sel_hi:[1,0]
	v_pk_mul_f32 v[18:19], v[18:19], v[98:99] op_sel_hi:[1,0]
	v_pk_mul_f32 v[16:17], v[16:17], v[98:99] op_sel_hi:[1,0]
	v_pk_mul_f32 v[14:15], v[14:15], v[98:99] op_sel_hi:[1,0]
	v_pk_mul_f32 v[12:13], v[12:13], v[98:99] op_sel_hi:[1,0]
	v_pk_mul_f32 v[10:11], v[10:11], v[98:99] op_sel_hi:[1,0]
	v_pk_mul_f32 v[8:9], v[8:9], v[98:99] op_sel_hi:[1,0]
	v_pk_mul_f32 v[6:7], v[6:7], v[98:99] op_sel_hi:[1,0]
	v_pk_mul_f32 v[4:5], v[4:5], v[98:99] op_sel_hi:[1,0]
	v_pk_mul_f32 v[2:3], v[2:3], v[98:99] op_sel_hi:[1,0]
	s_branch .LBB0_1596
